# odd-tile row-sum adds also moved behind the PV MFMAs (P fragment renamed to free staging registers)
# baseline (speedup 1.0000x reference)
; __device__ __forceinline__ void attn_tile(const u16* sb, const bf16x8 (&qa)[6], f32x16& o0, f32x16& o1, f32x16& lacc,
;                                           float& m, bool& mz, int r, int h, bool first) {
;     ...
;   float pa = 0.f, pb = 0.f, pc = 0.f, pd = 0.f;
; #pragma unroll
;   for (int i = 0; i < 16; ++i) {
;     s0[i] = __builtin_amdgcn_exp2f(s0[i]); s1[i] = __builtin_amdgcn_exp2f(s1[i]);
;     if ((i & 3) == 0) pa += s0[i] + s1[i];
;     else if ((i & 3) == 1) pb += s0[i] + s1[i];
;     else if ((i & 3) == 2) pc += s0[i] + s1[i];
;     else pd += s0[i] + s1[i];
;   }
;   lacc[0] += (pa + pb) + (pc + pd);
;   const u16* vp = sb + 64 * KLD + r * VLD + 8 * h;
;   __builtin_amdgcn_s_setprio(1);
; #pragma unroll
;   for (int kb = 0; kb < 2; ++kb) {
; #pragma unroll
;     for (int s = 0; s < 2; ++s) {
;       const bf16x8 pf = pack_p(kb == 0 ? s0 : s1, 8 * s);
;       const int koff = kb * 32 + 16 * s;
;       const bf16x8 v0 = *(const bf16x8*)(vp + koff);
;       const bf16x8 v1 = *(const bf16x8*)(vp + 32 * VLD + koff);
;       o0 = mfma32(v0, pf, o0);
;       o1 = mfma32(v1, pf, o1);
;     }
;   }
;   __builtin_amdgcn_s_setprio(0);
.LBB0_474:
	v_exp_f32_e32 v148, v35
	v_exp_f32_e32 v149, v36
	v_exp_f32_e32 v142, v38
	v_exp_f32_e32 v150, v39
	v_exp_f32_e32 v38, v51
	v_exp_f32_e32 v39, v52
	v_exp_f32_e32 v139, v53
	v_exp_f32_e32 v53, v41
	v_exp_f32_e32 v151, v40
	v_exp_f32_e32 v40, v55
	v_exp_f32_e32 v41, v56
	v_exp_f32_e32 v144, v42
	v_exp_f32_e32 v42, v43
	v_exp_f32_e32 v43, v44
	v_exp_f32_e32 v140, v50
	v_exp_f32_e32 v50, v59
	v_exp_f32_e32 v51, v60
	v_exp_f32_e32 v146, v46
	v_exp_f32_e32 v46, v47
	v_exp_f32_e32 v47, v48
	v_exp_f32_e32 v52, v54
	v_exp_f32_e32 v54, v63
	v_exp_f32_e32 v55, v64
	v_exp_f32_e32 v141, v37
	v_exp_f32_e32 v138, v34
	v_exp_f32_e32 v143, v57
	v_exp_f32_e32 v145, v61
	v_exp_f32_e32 v45, v45
	v_exp_f32_e32 v44, v58
	v_exp_f32_e32 v147, v65
	v_exp_f32_e32 v49, v49
	v_exp_f32_e32 v48, v62
	s_setprio 1
	v_cvt_pk_bf16_f32 v98, v140, v38
	v_cvt_pk_bf16_f32 v99, v39, v139
	v_cvt_pk_bf16_f32 v100, v52, v40
	v_cvt_pk_bf16_f32 v101, v41, v143
	v_cvt_pk_bf16_f32 v246, v44, v50
	v_cvt_pk_bf16_f32 v247, v51, v145
	v_cvt_pk_bf16_f32 v248, v48, v54
	v_cvt_pk_bf16_f32 v249, v55, v147
	s_waitcnt lgkmcnt(0)
	v_mfma_f32_32x32x16_bf16 v[18:33], v[214:217], v[98:101], v[18:33]
	v_mfma_f32_32x32x16_bf16 v[2:17], v[218:221], v[98:101], v[2:17]
	v_cvt_pk_bf16_f32 v98, v138, v148
	v_cvt_pk_bf16_f32 v99, v149, v141
	v_cvt_pk_bf16_f32 v100, v142, v150
	v_cvt_pk_bf16_f32 v101, v151, v53
	v_mfma_f32_32x32x16_bf16 v[18:33], v[222:225], v[246:249], v[18:33]
	v_mfma_f32_32x32x16_bf16 v[2:17], v[226:229], v[246:249], v[2:17]
	v_cvt_pk_bf16_f32 v246, v144, v42
	v_cvt_pk_bf16_f32 v247, v43, v45
	v_cvt_pk_bf16_f32 v248, v146, v46
	v_cvt_pk_bf16_f32 v249, v47, v49
	v_mfma_f32_32x32x16_bf16 v[18:33], v[230:233], v[98:101], v[18:33]
	v_mfma_f32_32x32x16_bf16 v[2:17], v[234:237], v[98:101], v[2:17]
	v_mfma_f32_32x32x16_bf16 v[18:33], v[238:241], v[246:249], v[18:33]
	v_mfma_f32_32x32x16_bf16 v[2:17], v[242:245], v[246:249], v[2:17]
	s_setprio 0
	v_pk_add_f32 v[34:35], v[38:39], v[148:149]
	v_pk_add_f32 v[36:37], v[40:41], v[150:151]
	v_pk_add_f32 v[34:35], v[36:37], v[34:35]
	v_pk_add_f32 v[36:37], v[50:51], v[42:43]
	v_pk_add_f32 v[34:35], v[36:37], v[34:35]
	v_pk_add_f32 v[36:37], v[54:55], v[46:47]
	v_pk_add_f32 v[56:57], v[52:53], v[142:143]
	v_pk_add_f32 v[34:35], v[36:37], v[34:35]
	v_pk_add_f32 v[36:37], v[140:141], v[138:139]
	s_nop 0
	s_nop 0
	v_pk_add_f32 v[36:37], v[56:57], v[36:37]
	v_pk_add_f32 v[56:57], v[44:45], v[144:145]
	s_nop 0
	v_pk_add_f32 v[36:37], v[56:57], v[36:37]
	v_pk_add_f32 v[56:57], v[48:49], v[146:147]
	s_nop 0
	v_pk_add_f32 v[36:37], v[56:57], v[36:37]
	s_nop 0
	v_pk_add_f32 v[34:35], v[34:35], v[36:37]
	s_nop 0
	v_add_f32_e32 v34, v34, v35
	v_add_f32_e32 v136, v136, v34
	s_andn2_b64 s[48:49], s[48:49], exec
	s_and_b64 s[50:51], s[50:51], exec
	s_or_b64 s[48:49], s[48:49], s[50:51]
